# scan producer trimmed: item-prologue weight loads de-serialised and the nine placeholder s_nop slots (left where two-byte-load waits used to be) removed from the per-step decay segment
# baseline (speedup 1.0000x reference)
; #define LAS __attribute__((address_space(3)))
; #define G2_BAR() do { asm volatile("s_waitcnt lgkmcnt(0)" ::: "memory"); __builtin_amdgcn_s_barrier(); asm volatile("" ::: "memory"); } while (0)
; __device__ __forceinline__ void gla_scan_phase2(LAS unsigned char* lds, const bf16_t* proj, const float* gbuf, const float* wgu  , const float* bg  ,
;                                                 bf16_t* ob0, bf16_t* ob1) {
;     ...
;                     if (dir == 0) {
; #pragma unroll
;                         for (int ii = 1; ii < 16; ++ii) cs[ii] += cs[ii - 1];
;                         *(LAS float*)(lds + G2_SEG + (seg * 128 + d) * 4) = cs[15];
;                     } else {
; #pragma unroll
;     ...
;                         *(LAS float*)(lds + G2_SEG + (seg * 128 + d) * 4) = cs[0];
;                     }
;                     G2_BAR();
;                     {
;                         const float t0 = *(const LAS float*)(lds + G2_SEG + d * 4), t1 = *(const LAS float*)(lds + G2_SEG + (128 + d) * 4);
;                         const float prefix = dir == 0 ? (seg ? t0 : 0.f) : (seg ? 0.f : t1);
;                         const float ebl = __builtin_amdgcn_exp2f(t0 + t1);
.LBB0_225:
	s_waitcnt vmcnt(6)
	ds_write_b32 v231, v115
	s_waitcnt lgkmcnt(0)
	s_barrier
	v_add_u32_e32 v25, s11, v202
	ds_read2st64_b32 v[104:105], v25 offset1:2
	ds_read_u16 v98, v173
	ds_read_u16 v100, v173 offset:256
	ds_read_u16 v94, v173 offset:512
	ds_read_u16 v96, v173 offset:768
	ds_read_u16 v90, v173 offset:1024
	ds_read_u16 v92, v173 offset:1280
	ds_read_u16 v82, v173 offset:1536
	ds_read_u16 v84, v173 offset:1792
	ds_read_u16 v99, v173 offset:8192
	ds_read_u16 v101, v173 offset:8448
	ds_read_u16 v95, v173 offset:8704
	ds_read_u16 v97, v173 offset:8960
	ds_read_u16 v91, v173 offset:9216
	ds_read_u16 v93, v173 offset:9472
	ds_read_u16 v83, v173 offset:9728
	ds_read_u16 v85, v173 offset:9984
	ds_read_u16 v86, v173 offset:2048
	ds_read_u16 v88, v173 offset:2304
	ds_read_u16 v78, v173 offset:2560
	ds_read_u16 v80, v173 offset:2816
	ds_read_u16 v74, v173 offset:3072
	ds_read_u16 v76, v173 offset:3328
	ds_read_u16 v70, v173 offset:3584
	ds_read_u16 v72, v173 offset:3840
	ds_read_u16 v87, v173 offset:10240
	ds_read_u16 v89, v173 offset:10496
	ds_read_u16 v79, v173 offset:10752
	ds_read_u16 v81, v173 offset:11008
	ds_read_u16 v75, v173 offset:11264
	ds_read_u16 v77, v173 offset:11520
	ds_read_u16 v71, v173 offset:11776
	ds_read_u16 v73, v173 offset:12032
	s_bitcmp1_b32 s20, 0
	s_cselect_b32 s0, 0xa800, 0
	s_waitcnt lgkmcnt(0)
	v_lshlrev_b32_e32 v111, 16, v100
	s_add_i32 s15, s0, 0
	s_waitcnt lgkmcnt(0)
; #define LAS __attribute__((address_space(3)))
; __device__ __forceinline__ unsigned pk2(float lo, float hi) { f32x2 v = {lo, hi}; bf16x2_t b = __builtin_convertvector(v, bf16x2_t); return __builtin_bit_cast(unsigned, b); }
; __device__ __forceinline__ float bf2f(unsigned u16) { return __uint_as_float(u16 << 16); }
; __device__ __forceinline__ void gla_scan_phase2(LAS unsigned char* lds, const bf16_t* proj, const float* gbuf, const float* wgu  , const float* bg  ,
;                                                 bf16_t* ob0, bf16_t* ob1) {
;     ...
;                         unsigned kd[8];
; #pragma unroll
;                         for (int ii = 0; ii < 16; ii += 2) {
;                             const float e0 = __builtin_amdgcn_exp2f(prefix + cs[ii]), e1 = __builtin_amdgcn_exp2f(prefix + cs[ii + 1]);
;                             const float q0 = bf2f(qv[ii]), q1 = bf2f(qv[ii + 1]);
;                             const float k0 = bf2f(kv[ii]) * __builtin_amdgcn_rcpf(e0), k1 = bf2f(kv[ii + 1]) * __builtin_amdgcn_rcpf(e1);
;                             const unsigned qd = pk2(q0 * e0, q1 * e1);
;                             const unsigned ki = pk2(k0, k1);
;                             kd[ii >> 1] = pk2(k0 * ebl, k1 * ebl);
;                             const int i0 = 16 * seg + ii;
;                             *(LAS unsigned short*)(set + G2_QD + i0 * 272 + d * 2) = (unsigned short)(qd & 0xffffu);
;                             *(LAS unsigned short*)(set + G2_QD + (i0 + 1) * 272 + d * 2) = (unsigned short)(qd >> 16);
;                             *(LAS unsigned short*)(lds + G2_KI + i0 * 272 + d * 2) = (unsigned short)(ki & 0xffffu);
;                             *(LAS unsigned short*)(lds + G2_KI + (i0 + 1) * 272 + d * 2) = (unsigned short)(ki >> 16);
;                         }
;                         *(LAS u32x4*)(set + G2_KDT + d * 80 + seg * 32) = (u32x4){kd[0], kd[1], kd[2], kd[3]};
;                         *(LAS u32x4*)(set + G2_KDT + d * 80 + seg * 32 + 16) = (u32x4){kd[4], kd[5], kd[6], kd[7]};
;                         if (seg == 0) *(LAS float*)(set + G2_EBL + d * 4) = ebl;
	v_cndmask_b32_e64 v25, v104, 0, s[38:39]
	v_cndmask_b32_e64 v26, 0, v105, s[38:39]
	v_cndmask_b32_e64 v102, v26, v25, s[48:49]
	v_add_f32_e32 v16, v16, v102
	v_exp_f32_e32 v108, v16
	v_add_f32_e32 v16, v110, v102
	v_exp_f32_e32 v109, v16
	v_add_f32_e32 v16, v104, v105
	v_rcp_f32_e32 v104, v108
	v_lshlrev_b32_e32 v110, 16, v98
	v_rcp_f32_e32 v105, v109
	v_pk_mul_f32 v[108:109], v[108:109], v[110:111]
	v_lshlrev_b32_e32 v101, 16, v101
	v_cvt_pk_bf16_f32 v25, v108, v109
	v_add3_u32 v108, s15, v201, v211
	v_lshlrev_b32_e32 v100, 16, v99
	ds_write_b16 v108, v25
	ds_write_b16_d16_hi v108, v25 offset:272
	v_add_f32_e32 v25, v107, v102
	v_pk_mul_f32 v[98:99], v[104:105], v[100:101]
	v_exp_f32_e32 v100, v25
	v_add_f32_e32 v25, v106, v102
	v_exp_f32_e32 v101, v25
	v_lshlrev_b32_e32 v107, 16, v96
	v_lshlrev_b32_e32 v106, 16, v94
	v_rcp_f32_e32 v104, v100
	v_rcp_f32_e32 v105, v101
	v_pk_mul_f32 v[100:101], v[100:101], v[106:107]
	v_cvt_pk_bf16_f32 v26, v98, v99
	v_cvt_pk_bf16_f32 v25, v100, v101
	ds_write_b16 v232, v26
	ds_write_b16_d16_hi v232, v26 offset:272
	ds_write_b16 v108, v25 offset:544
	ds_write_b16_d16_hi v108, v25 offset:816
	v_add_f32_e32 v25, v103, v102
	v_exp_f32_e32 v16, v16
	v_exp_f32_e32 v30, v25
	v_add_f32_e32 v25, v31, v102
	v_exp_f32_e32 v31, v25
	v_lshlrev_b32_e32 v97, 16, v97
	v_lshlrev_b32_e32 v96, 16, v95
	v_pk_mul_f32 v[94:95], v[104:105], v[96:97]
	v_pk_mul_f32 v[98:99], v[16:17], v[98:99] op_sel_hi:[0,1]
	v_cvt_pk_bf16_f32 v26, v94, v95
	v_pk_mul_f32 v[94:95], v[16:17], v[94:95] op_sel_hi:[0,1]
	v_lshlrev_b32_e32 v97, 16, v92
	v_lshlrev_b32_e32 v96, 16, v90
	v_cvt_pk_bf16_f32 v98, v98, v99
	v_cvt_pk_bf16_f32 v99, v94, v95
	v_rcp_f32_e32 v94, v30
	v_rcp_f32_e32 v95, v31
	v_pk_mul_f32 v[30:31], v[30:31], v[96:97]
	ds_write_b16 v232, v26 offset:544
	ds_write_b16_d16_hi v232, v26 offset:816
	v_cvt_pk_bf16_f32 v25, v30, v31
	ds_write_b16 v108, v25 offset:1088
	ds_write_b16_d16_hi v108, v25 offset:1360
	v_add_f32_e32 v25, v28, v102
	v_exp_f32_e32 v26, v25
	v_add_f32_e32 v25, v27, v102
	v_exp_f32_e32 v27, v25
	v_lshlrev_b32_e32 v31, 16, v93
	v_lshlrev_b32_e32 v30, 16, v91
	v_pk_mul_f32 v[30:31], v[94:95], v[30:31]
	v_rcp_f32_e32 v28, v26
	v_cvt_pk_bf16_f32 v29, v30, v31
	v_pk_mul_f32 v[30:31], v[16:17], v[30:31] op_sel_hi:[0,1]
	v_cvt_pk_bf16_f32 v100, v30, v31
	ds_write_b16 v232, v29 offset:1088
	ds_write_b16_d16_hi v232, v29 offset:1360
	v_rcp_f32_e32 v29, v27
	v_lshlrev_b32_e32 v31, 16, v84
	v_lshlrev_b32_e32 v30, 16, v82
	v_pk_mul_f32 v[26:27], v[26:27], v[30:31]
	v_add_f32_e32 v24, v24, v102
	v_cvt_pk_bf16_f32 v25, v26, v27
	v_add_f32_e32 v23, v23, v102
	v_lshlrev_b32_e32 v27, 16, v85
	v_lshlrev_b32_e32 v26, 16, v83
	ds_write_b16 v108, v25 offset:1632
	ds_write_b16_d16_hi v108, v25 offset:1904
	v_exp_f32_e32 v24, v24
	v_exp_f32_e32 v25, v23
	v_pk_mul_f32 v[26:27], v[28:29], v[26:27]
	v_lshlrev_b32_e32 v29, 16, v88
	v_cvt_pk_bf16_f32 v28, v26, v27
	v_pk_mul_f32 v[26:27], v[16:17], v[26:27] op_sel_hi:[0,1]
	ds_write_b16 v232, v28 offset:1632
	ds_write_b16_d16_hi v232, v28 offset:1904
	v_lshlrev_b32_e32 v28, 16, v86
	v_cvt_pk_bf16_f32 v101, v26, v27
	v_rcp_f32_e32 v26, v24
	v_rcp_f32_e32 v27, v25
	v_pk_mul_f32 v[24:25], v[24:25], v[28:29]
	v_add_f32_e32 v22, v22, v102
	v_cvt_pk_bf16_f32 v23, v24, v25
	v_add_f32_e32 v21, v21, v102
	ds_write_b16 v108, v23 offset:2176
	ds_write_b16_d16_hi v108, v23 offset:2448
	v_exp_f32_e32 v22, v22
	v_exp_f32_e32 v23, v21
	v_lshlrev_b32_e32 v25, 16, v89
	v_lshlrev_b32_e32 v24, 16, v87
	v_pk_mul_f32 v[24:25], v[26:27], v[24:25]
	v_lshlrev_b32_e32 v29, 16, v80
	v_cvt_pk_bf16_f32 v26, v24, v25
	v_lshlrev_b32_e32 v28, 16, v78
	ds_write_b16 v232, v26 offset:2176
	ds_write_b16_d16_hi v232, v26 offset:2448
	v_rcp_f32_e32 v26, v22
	v_rcp_f32_e32 v27, v23
	v_pk_mul_f32 v[22:23], v[22:23], v[28:29]
	v_add_f32_e32 v20, v20, v102
	v_cvt_pk_bf16_f32 v21, v22, v23
	v_add_f32_e32 v19, v19, v102
	ds_write_b16 v108, v21 offset:2720
	ds_write_b16_d16_hi v108, v21 offset:2992
	v_exp_f32_e32 v20, v20
	v_exp_f32_e32 v21, v19
	v_lshlrev_b32_e32 v23, 16, v81
	v_lshlrev_b32_e32 v22, 16, v79
	v_pk_mul_f32 v[22:23], v[26:27], v[22:23]
	v_pk_mul_f32 v[24:25], v[16:17], v[24:25] op_sel_hi:[0,1]
	v_cvt_pk_bf16_f32 v26, v22, v23
	v_pk_mul_f32 v[22:23], v[16:17], v[22:23] op_sel_hi:[0,1]
	v_cvt_pk_bf16_f32 v24, v24, v25
	v_cvt_pk_bf16_f32 v25, v22, v23
	v_rcp_f32_e32 v22, v20
	v_rcp_f32_e32 v23, v21
	ds_write_b16 v232, v26 offset:2720
	ds_write_b16_d16_hi v232, v26 offset:2992
	v_lshlrev_b32_e32 v27, 16, v76
	v_lshlrev_b32_e32 v26, 16, v74
	v_pk_mul_f32 v[20:21], v[20:21], v[26:27]
	v_add_f32_e32 v18, v18, v102
	v_cvt_pk_bf16_f32 v19, v20, v21
	v_lshlrev_b32_e32 v21, 16, v77
	v_lshlrev_b32_e32 v20, 16, v75
	v_pk_mul_f32 v[20:21], v[22:23], v[20:21]
	ds_write_b16 v108, v19 offset:3264
	ds_write_b16_d16_hi v108, v19 offset:3536
	v_cvt_pk_bf16_f32 v22, v20, v21
	v_pk_mul_f32 v[20:21], v[16:17], v[20:21] op_sel_hi:[0,1]
	v_add_f32_e32 v17, v17, v102
	v_exp_f32_e32 v18, v18
	v_exp_f32_e32 v19, v17
	v_cvt_pk_bf16_f32 v26, v20, v21
	ds_write_b16 v232, v22 offset:3264
	ds_write_b16_d16_hi v232, v22 offset:3536
	v_rcp_f32_e32 v20, v18
	v_rcp_f32_e32 v21, v19
	v_lshlrev_b32_e32 v23, 16, v72
	v_lshlrev_b32_e32 v22, 16, v70
	v_pk_mul_f32 v[18:19], v[18:19], v[22:23]
	s_nop 0
	v_cvt_pk_bf16_f32 v17, v18, v19
	v_lshlrev_b32_e32 v19, 16, v73
	v_lshlrev_b32_e32 v18, 16, v71
	v_pk_mul_f32 v[18:19], v[20:21], v[18:19]
	s_nop 0
	v_cvt_pk_bf16_f32 v20, v18, v19
	v_pk_mul_f32 v[18:19], v[16:17], v[18:19] op_sel_hi:[0,1]
	ds_write_b16 v108, v17 offset:3808
	ds_write_b16_d16_hi v108, v17 offset:4080
	ds_write_b16 v232, v20 offset:3808
	ds_write_b16_d16_hi v232, v20 offset:4080
	v_add3_u32 v17, s15, v203, v204
	v_cvt_pk_bf16_f32 v27, v18, v19
	ds_write_b128 v17, v[98:101] offset:8704
	ds_write_b128 v17, v[24:27] offset:8720
	s_and_saveexec_b64 s[6:7], s[38:39]
	s_cbranch_execz .LBB0_219
	v_add_u32_e32 v17, s15, v202
	ds_write_b32 v17, v16 offset:41984
	s_branch .LBB0_219
